# up-GEMM ConvFFN epilogue rewritten with packed f32 VALU (v_pk_mul/fma/add_f32), same arithmetic, half the VALU instructions
# speedup vs baseline: 1.0284x; 1.0079x over previous
; DEV u32x4 pack8(const float (&f)[8]) { u32x4 w; w.x = cvt_pk_bf16(f[0], f[1]); w.y = cvt_pk_bf16(f[2], f[3]); w.z = cvt_pk_bf16(f[4], f[5]); w.w = cvt_pk_bf16(f[6], f[7]); return w; }
; DEV float gelu_t(float x) { const float u = x * (0.7978845608f + 0.0356774081f * x * x); return x * __builtin_amdgcn_rcpf(1.f + __builtin_amdgcn_exp2f(-2.885390082f * u)); }
;     DEV bool operator()(f32x4 (&acc)[2][2][4][2], const Unit& u, int wr, int wc, int fr, int fq) const {
;     ...
;         bf16_t* outp = ACT + ((size_t)u.pm * BM + (size_t)(16 * wr + fr) * 8) * DFF + ch0;
; #pragma unroll
;         for (int i = 0; i < 8; ++i) { float y[8];
; #pragma unroll
;             for (int c = 0; c < 8; ++c) {
;                 const float g0 = acc[i >> 2][0][i & 3][c >> 2][c & 3];
;                 const float gm1 = i >= 1 ? acc[(i - 1 < 0 ? 0 : i - 1) >> 2][0][(i - 1 < 0 ? 0 : i - 1) & 3][c >> 2][c & 3] : p7[c];
;                 const float gm2 = i >= 2 ? acc[(i - 2 < 0 ? 0 : i - 2) >> 2][0][(i - 2 < 0 ? 0 : i - 2) & 3][c >> 2][c & 3] : (i == 0 ? p6[c] : p7[c]);
;                 y[c] = gelu_t(w[0][c] * gm2 + w[1][c] * gm1 + w[2][c] * g0) * acc[i >> 2][1][i & 3][c >> 2][c & 3]; }
;             if (!(halo && i < 2)) *(u32x4*)(outp + (size_t)i * DFF) = pack8(y); }
.LBB0_37:
	s_or_b64 exec, exec, s[4:5]
	v_mov_b32_e32 v194, 0x180000
	v_mad_i64_i32 v[194:195], s[4:5], s64, v194, v[186:187]
	v_lshl_add_u64 v[192:193], v[192:193], 1, v[194:195]
	s_waitcnt vmcnt(0) lgkmcnt(0)
	v_mov_b32_e32 v236, 0x3d122279
	v_mov_b32_e32 v237, 0x3f4c422a
	v_mov_b32_e32 v238, 0xc038aa3b
	v_mov_b32_e32 v239, 1.0
	v_pk_mul_f32 v[202:203], v[134:135], v[166:167]
	v_pk_mul_f32 v[204:205], v[136:137], v[168:169]
	v_pk_mul_f32 v[206:207], v[122:123], v[162:163]
	v_pk_mul_f32 v[208:209], v[124:125], v[164:165]
	v_pk_fma_f32 v[202:203], v[78:79], v[158:159], v[202:203]
	v_pk_fma_f32 v[204:205], v[80:81], v[160:161], v[204:205]
	v_pk_fma_f32 v[206:207], v[62:63], v[154:155], v[206:207]
	v_pk_fma_f32 v[208:209], v[64:65], v[156:157], v[208:209]
	v_pk_fma_f32 v[194:195], v[82:83], v[130:131], v[202:203]
	v_pk_fma_f32 v[196:197], v[84:85], v[132:133], v[204:205]
	v_pk_fma_f32 v[198:199], v[66:67], v[118:119], v[206:207]
	v_pk_fma_f32 v[200:201], v[68:69], v[120:121], v[208:209]
	v_pk_mul_f32 v[202:203], v[194:195], v[236:237] op_sel_hi:[1,0]
	v_pk_mul_f32 v[204:205], v[196:197], v[236:237] op_sel_hi:[1,0]
	v_pk_mul_f32 v[206:207], v[198:199], v[236:237] op_sel_hi:[1,0]
	v_pk_mul_f32 v[208:209], v[200:201], v[236:237] op_sel_hi:[1,0]
	v_pk_fma_f32 v[202:203], v[194:195], v[202:203], v[236:237] op_sel:[0,0,1] op_sel_hi:[1,1,1]
	v_pk_fma_f32 v[204:205], v[196:197], v[204:205], v[236:237] op_sel:[0,0,1] op_sel_hi:[1,1,1]
	v_pk_fma_f32 v[206:207], v[198:199], v[206:207], v[236:237] op_sel:[0,0,1] op_sel_hi:[1,1,1]
	v_pk_fma_f32 v[208:209], v[200:201], v[208:209], v[236:237] op_sel:[0,0,1] op_sel_hi:[1,1,1]
	v_pk_mul_f32 v[202:203], v[194:195], v[202:203]
	v_pk_mul_f32 v[204:205], v[196:197], v[204:205]
	v_pk_mul_f32 v[206:207], v[198:199], v[206:207]
	v_pk_mul_f32 v[208:209], v[200:201], v[208:209]
	v_pk_mul_f32 v[202:203], v[202:203], v[238:239] op_sel_hi:[1,0]
	v_pk_mul_f32 v[204:205], v[204:205], v[238:239] op_sel_hi:[1,0]
	v_pk_mul_f32 v[206:207], v[206:207], v[238:239] op_sel_hi:[1,0]
	v_pk_mul_f32 v[208:209], v[208:209], v[238:239] op_sel_hi:[1,0]
	v_exp_f32_e32 v202, v202
	v_exp_f32_e32 v203, v203
	v_exp_f32_e32 v204, v204
	v_exp_f32_e32 v205, v205
	v_exp_f32_e32 v206, v206
	v_exp_f32_e32 v207, v207
	v_exp_f32_e32 v208, v208
	v_exp_f32_e32 v209, v209
	v_pk_add_f32 v[202:203], v[202:203], v[238:239] op_sel:[0,1] op_sel_hi:[1,1]
	v_pk_add_f32 v[204:205], v[204:205], v[238:239] op_sel:[0,1] op_sel_hi:[1,1]
	v_pk_add_f32 v[206:207], v[206:207], v[238:239] op_sel:[0,1] op_sel_hi:[1,1]
	v_pk_add_f32 v[208:209], v[208:209], v[238:239] op_sel:[0,1] op_sel_hi:[1,1]
	v_rcp_f32_e32 v202, v202
	v_rcp_f32_e32 v203, v203
	v_rcp_f32_e32 v204, v204
	v_rcp_f32_e32 v205, v205
	v_rcp_f32_e32 v206, v206
	v_rcp_f32_e32 v207, v207
	v_rcp_f32_e32 v208, v208
	v_rcp_f32_e32 v209, v209
	v_pk_mul_f32 v[194:195], v[194:195], v[202:203]
	v_pk_mul_f32 v[196:197], v[196:197], v[204:205]
	v_pk_mul_f32 v[198:199], v[198:199], v[206:207]
	v_pk_mul_f32 v[200:201], v[200:201], v[208:209]
	v_pk_mul_f32 v[150:151], v[150:151], v[194:195]
	v_pk_mul_f32 v[152:153], v[152:153], v[196:197]
	v_pk_mul_f32 v[146:147], v[146:147], v[198:199]
	v_pk_mul_f32 v[148:149], v[148:149], v[200:201]
	v_cvt_pk_bf16_f32 v150, v150, v151
	v_cvt_pk_bf16_f32 v151, v152, v153
	v_cvt_pk_bf16_f32 v152, v146, v147
	v_cvt_pk_bf16_f32 v153, v148, v149
	s_mov_b64 s[4:5], exec
	s_and_b64 exec, exec, s[42:43]
	global_store_dwordx4 v[192:193], v[150:153], off
	s_mov_b64 exec, s[4:5]
	v_pk_mul_f32 v[202:203], v[134:135], v[158:159]
	v_pk_mul_f32 v[204:205], v[136:137], v[160:161]
	v_pk_mul_f32 v[206:207], v[122:123], v[154:155]
	v_pk_mul_f32 v[208:209], v[124:125], v[156:157]
	s_mov_b64 s[6:7], 0x1800
	v_lshl_add_u64 v[234:235], v[192:193], 0, s[6:7]
	v_pk_fma_f32 v[202:203], v[78:79], v[130:131], v[202:203]
	v_pk_fma_f32 v[204:205], v[80:81], v[132:133], v[204:205]
	v_pk_fma_f32 v[206:207], v[62:63], v[118:119], v[206:207]
	v_pk_fma_f32 v[208:209], v[64:65], v[120:121], v[208:209]
	v_pk_fma_f32 v[194:195], v[82:83], v[110:111], v[202:203]
	v_pk_fma_f32 v[196:197], v[84:85], v[112:113], v[204:205]
	v_pk_fma_f32 v[198:199], v[66:67], v[102:103], v[206:207]
	v_pk_fma_f32 v[200:201], v[68:69], v[104:105], v[208:209]
	v_pk_mul_f32 v[202:203], v[194:195], v[236:237] op_sel_hi:[1,0]
	v_pk_mul_f32 v[204:205], v[196:197], v[236:237] op_sel_hi:[1,0]
	v_pk_mul_f32 v[206:207], v[198:199], v[236:237] op_sel_hi:[1,0]
	v_pk_mul_f32 v[208:209], v[200:201], v[236:237] op_sel_hi:[1,0]
	v_pk_fma_f32 v[202:203], v[194:195], v[202:203], v[236:237] op_sel:[0,0,1] op_sel_hi:[1,1,1]
	v_pk_fma_f32 v[204:205], v[196:197], v[204:205], v[236:237] op_sel:[0,0,1] op_sel_hi:[1,1,1]
	v_pk_fma_f32 v[206:207], v[198:199], v[206:207], v[236:237] op_sel:[0,0,1] op_sel_hi:[1,1,1]
	v_pk_fma_f32 v[208:209], v[200:201], v[208:209], v[236:237] op_sel:[0,0,1] op_sel_hi:[1,1,1]
	v_pk_mul_f32 v[202:203], v[194:195], v[202:203]
	v_pk_mul_f32 v[204:205], v[196:197], v[204:205]
	v_pk_mul_f32 v[206:207], v[198:199], v[206:207]
	v_pk_mul_f32 v[208:209], v[200:201], v[208:209]
	v_pk_mul_f32 v[202:203], v[202:203], v[238:239] op_sel_hi:[1,0]
	v_pk_mul_f32 v[204:205], v[204:205], v[238:239] op_sel_hi:[1,0]
	v_pk_mul_f32 v[206:207], v[206:207], v[238:239] op_sel_hi:[1,0]
	v_pk_mul_f32 v[208:209], v[208:209], v[238:239] op_sel_hi:[1,0]
	v_exp_f32_e32 v202, v202
	v_exp_f32_e32 v203, v203
	v_exp_f32_e32 v204, v204
	v_exp_f32_e32 v205, v205
	v_exp_f32_e32 v206, v206
	v_exp_f32_e32 v207, v207
	v_exp_f32_e32 v208, v208
	v_exp_f32_e32 v209, v209
	v_pk_add_f32 v[202:203], v[202:203], v[238:239] op_sel:[0,1] op_sel_hi:[1,1]
; DEV u32x4 pack8(const float (&f)[8]) { u32x4 w; w.x = cvt_pk_bf16(f[0], f[1]); w.y = cvt_pk_bf16(f[2], f[3]); w.z = cvt_pk_bf16(f[4], f[5]); w.w = cvt_pk_bf16(f[6], f[7]); return w; }
; DEV float gelu_t(float x) { const float u = x * (0.7978845608f + 0.0356774081f * x * x); return x * __builtin_amdgcn_rcpf(1.f + __builtin_amdgcn_exp2f(-2.885390082f * u)); }
;     DEV bool operator()(f32x4 (&acc)[2][2][4][2], const Unit& u, int wr, int wc, int fr, int fq) const {
;     ...
;         for (int i = 0; i < 8; ++i) { float y[8];
; #pragma unroll
;             for (int c = 0; c < 8; ++c) {
;                 const float g0 = acc[i >> 2][0][i & 3][c >> 2][c & 3];
;                 const float gm1 = i >= 1 ? acc[(i - 1 < 0 ? 0 : i - 1) >> 2][0][(i - 1 < 0 ? 0 : i - 1) & 3][c >> 2][c & 3] : p7[c];
;                 const float gm2 = i >= 2 ? acc[(i - 2 < 0 ? 0 : i - 2) >> 2][0][(i - 2 < 0 ? 0 : i - 2) & 3][c >> 2][c & 3] : (i == 0 ? p6[c] : p7[c]);
;                 y[c] = gelu_t(w[0][c] * gm2 + w[1][c] * gm1 + w[2][c] * g0) * acc[i >> 2][1][i & 3][c >> 2][c & 3]; }
;             if (!(halo && i < 2)) *(u32x4*)(outp + (size_t)i * DFF) = pack8(y); }
	v_pk_add_f32 v[204:205], v[204:205], v[238:239] op_sel:[0,1] op_sel_hi:[1,1]
	v_pk_add_f32 v[206:207], v[206:207], v[238:239] op_sel:[0,1] op_sel_hi:[1,1]
	v_pk_add_f32 v[208:209], v[208:209], v[238:239] op_sel:[0,1] op_sel_hi:[1,1]
	v_rcp_f32_e32 v202, v202
	v_rcp_f32_e32 v203, v203
	v_rcp_f32_e32 v204, v204
	v_rcp_f32_e32 v205, v205
	v_rcp_f32_e32 v206, v206
	v_rcp_f32_e32 v207, v207
	v_rcp_f32_e32 v208, v208
	v_rcp_f32_e32 v209, v209
	v_pk_mul_f32 v[194:195], v[194:195], v[202:203]
	v_pk_mul_f32 v[196:197], v[196:197], v[204:205]
	v_pk_mul_f32 v[198:199], v[198:199], v[206:207]
	v_pk_mul_f32 v[200:201], v[200:201], v[208:209]
	v_pk_mul_f32 v[142:143], v[142:143], v[194:195]
	v_pk_mul_f32 v[144:145], v[144:145], v[196:197]
	v_pk_mul_f32 v[138:139], v[138:139], v[198:199]
	v_pk_mul_f32 v[140:141], v[140:141], v[200:201]
	v_cvt_pk_bf16_f32 v142, v142, v143
	v_cvt_pk_bf16_f32 v143, v144, v145
	v_cvt_pk_bf16_f32 v144, v138, v139
	v_cvt_pk_bf16_f32 v145, v140, v141
	s_mov_b64 s[4:5], exec
	s_and_b64 exec, exec, s[42:43]
	global_store_dwordx4 v[234:235], v[142:145], off
	s_mov_b64 exec, s[4:5]
	v_pk_mul_f32 v[202:203], v[134:135], v[130:131]
	v_pk_mul_f32 v[204:205], v[136:137], v[132:133]
	v_pk_mul_f32 v[206:207], v[122:123], v[118:119]
	v_pk_mul_f32 v[208:209], v[124:125], v[120:121]
	s_mov_b64 s[6:7], 0x3000
	v_lshl_add_u64 v[232:233], v[192:193], 0, s[6:7]
	v_pk_fma_f32 v[202:203], v[78:79], v[110:111], v[202:203]
	v_pk_fma_f32 v[204:205], v[80:81], v[112:113], v[204:205]
	v_pk_fma_f32 v[206:207], v[62:63], v[102:103], v[206:207]
	v_pk_fma_f32 v[208:209], v[64:65], v[104:105], v[208:209]
	v_pk_fma_f32 v[194:195], v[82:83], v[94:95], v[202:203]
	v_pk_fma_f32 v[196:197], v[84:85], v[96:97], v[204:205]
	v_pk_fma_f32 v[198:199], v[66:67], v[86:87], v[206:207]
	v_pk_fma_f32 v[200:201], v[68:69], v[88:89], v[208:209]
	v_pk_mul_f32 v[202:203], v[194:195], v[236:237] op_sel_hi:[1,0]
	v_pk_mul_f32 v[204:205], v[196:197], v[236:237] op_sel_hi:[1,0]
	v_pk_mul_f32 v[206:207], v[198:199], v[236:237] op_sel_hi:[1,0]
	v_pk_mul_f32 v[208:209], v[200:201], v[236:237] op_sel_hi:[1,0]
	v_pk_fma_f32 v[202:203], v[194:195], v[202:203], v[236:237] op_sel:[0,0,1] op_sel_hi:[1,1,1]
	v_pk_fma_f32 v[204:205], v[196:197], v[204:205], v[236:237] op_sel:[0,0,1] op_sel_hi:[1,1,1]
	v_pk_fma_f32 v[206:207], v[198:199], v[206:207], v[236:237] op_sel:[0,0,1] op_sel_hi:[1,1,1]
	v_pk_fma_f32 v[208:209], v[200:201], v[208:209], v[236:237] op_sel:[0,0,1] op_sel_hi:[1,1,1]
	v_pk_mul_f32 v[202:203], v[194:195], v[202:203]
	v_pk_mul_f32 v[204:205], v[196:197], v[204:205]
	v_pk_mul_f32 v[206:207], v[198:199], v[206:207]
	v_pk_mul_f32 v[208:209], v[200:201], v[208:209]
	v_pk_mul_f32 v[202:203], v[202:203], v[238:239] op_sel_hi:[1,0]
	v_pk_mul_f32 v[204:205], v[204:205], v[238:239] op_sel_hi:[1,0]
	v_pk_mul_f32 v[206:207], v[206:207], v[238:239] op_sel_hi:[1,0]
	v_pk_mul_f32 v[208:209], v[208:209], v[238:239] op_sel_hi:[1,0]
	v_exp_f32_e32 v202, v202
	v_exp_f32_e32 v203, v203
	v_exp_f32_e32 v204, v204
	v_exp_f32_e32 v205, v205
	v_exp_f32_e32 v206, v206
	v_exp_f32_e32 v207, v207
	v_exp_f32_e32 v208, v208
	v_exp_f32_e32 v209, v209
	v_pk_add_f32 v[202:203], v[202:203], v[238:239] op_sel:[0,1] op_sel_hi:[1,1]
	v_pk_add_f32 v[204:205], v[204:205], v[238:239] op_sel:[0,1] op_sel_hi:[1,1]
	v_pk_add_f32 v[206:207], v[206:207], v[238:239] op_sel:[0,1] op_sel_hi:[1,1]
	v_pk_add_f32 v[208:209], v[208:209], v[238:239] op_sel:[0,1] op_sel_hi:[1,1]
	v_rcp_f32_e32 v202, v202
	v_rcp_f32_e32 v203, v203
	v_rcp_f32_e32 v204, v204
	v_rcp_f32_e32 v205, v205
	v_rcp_f32_e32 v206, v206
	v_rcp_f32_e32 v207, v207
	v_rcp_f32_e32 v208, v208
	v_rcp_f32_e32 v209, v209
	v_pk_mul_f32 v[194:195], v[194:195], v[202:203]
	v_pk_mul_f32 v[196:197], v[196:197], v[204:205]
	v_pk_mul_f32 v[198:199], v[198:199], v[206:207]
	v_pk_mul_f32 v[200:201], v[200:201], v[208:209]
	v_pk_mul_f32 v[126:127], v[126:127], v[194:195]
	v_pk_mul_f32 v[128:129], v[128:129], v[196:197]
	v_pk_mul_f32 v[114:115], v[114:115], v[198:199]
	v_pk_mul_f32 v[116:117], v[116:117], v[200:201]
	v_cvt_pk_bf16_f32 v126, v126, v127
	v_cvt_pk_bf16_f32 v127, v128, v129
	v_cvt_pk_bf16_f32 v128, v114, v115
	v_cvt_pk_bf16_f32 v129, v116, v117
	global_store_dwordx4 v[232:233], v[126:129], off
	v_pk_mul_f32 v[202:203], v[134:135], v[110:111]
	v_pk_mul_f32 v[204:205], v[136:137], v[112:113]
	v_pk_mul_f32 v[206:207], v[122:123], v[102:103]
	v_pk_mul_f32 v[208:209], v[124:125], v[104:105]
	s_mov_b64 s[6:7], 0x4800
	v_lshl_add_u64 v[234:235], v[192:193], 0, s[6:7]
	v_pk_fma_f32 v[202:203], v[78:79], v[94:95], v[202:203]
	v_pk_fma_f32 v[204:205], v[80:81], v[96:97], v[204:205]
	v_pk_fma_f32 v[206:207], v[62:63], v[86:87], v[206:207]
	v_pk_fma_f32 v[208:209], v[64:65], v[88:89], v[208:209]
	v_pk_fma_f32 v[194:195], v[82:83], v[70:71], v[202:203]
	v_pk_fma_f32 v[196:197], v[84:85], v[72:73], v[204:205]
	v_pk_fma_f32 v[198:199], v[66:67], v[54:55], v[206:207]
	v_pk_fma_f32 v[200:201], v[68:69], v[56:57], v[208:209]
	v_pk_mul_f32 v[202:203], v[194:195], v[236:237] op_sel_hi:[1,0]
	v_pk_mul_f32 v[204:205], v[196:197], v[236:237] op_sel_hi:[1,0]
	v_pk_mul_f32 v[206:207], v[198:199], v[236:237] op_sel_hi:[1,0]
	v_pk_mul_f32 v[208:209], v[200:201], v[236:237] op_sel_hi:[1,0]
	v_pk_fma_f32 v[202:203], v[194:195], v[202:203], v[236:237] op_sel:[0,0,1] op_sel_hi:[1,1,1]
	v_pk_fma_f32 v[204:205], v[196:197], v[204:205], v[236:237] op_sel:[0,0,1] op_sel_hi:[1,1,1]
	v_pk_fma_f32 v[206:207], v[198:199], v[206:207], v[236:237] op_sel:[0,0,1] op_sel_hi:[1,1,1]
	v_pk_fma_f32 v[208:209], v[200:201], v[208:209], v[236:237] op_sel:[0,0,1] op_sel_hi:[1,1,1]
	v_pk_mul_f32 v[202:203], v[194:195], v[202:203]
; DEV u32x4 pack8(const float (&f)[8]) { u32x4 w; w.x = cvt_pk_bf16(f[0], f[1]); w.y = cvt_pk_bf16(f[2], f[3]); w.z = cvt_pk_bf16(f[4], f[5]); w.w = cvt_pk_bf16(f[6], f[7]); return w; }
; DEV float gelu_t(float x) { const float u = x * (0.7978845608f + 0.0356774081f * x * x); return x * __builtin_amdgcn_rcpf(1.f + __builtin_amdgcn_exp2f(-2.885390082f * u)); }
;     DEV bool operator()(f32x4 (&acc)[2][2][4][2], const Unit& u, int wr, int wc, int fr, int fq) const {
;     ...
;         for (int i = 0; i < 8; ++i) { float y[8];
; #pragma unroll
;             for (int c = 0; c < 8; ++c) {
;                 const float g0 = acc[i >> 2][0][i & 3][c >> 2][c & 3];
;                 const float gm1 = i >= 1 ? acc[(i - 1 < 0 ? 0 : i - 1) >> 2][0][(i - 1 < 0 ? 0 : i - 1) & 3][c >> 2][c & 3] : p7[c];
;                 const float gm2 = i >= 2 ? acc[(i - 2 < 0 ? 0 : i - 2) >> 2][0][(i - 2 < 0 ? 0 : i - 2) & 3][c >> 2][c & 3] : (i == 0 ? p6[c] : p7[c]);
;                 y[c] = gelu_t(w[0][c] * gm2 + w[1][c] * gm1 + w[2][c] * g0) * acc[i >> 2][1][i & 3][c >> 2][c & 3]; }
;             if (!(halo && i < 2)) *(u32x4*)(outp + (size_t)i * DFF) = pack8(y); }
	v_pk_mul_f32 v[204:205], v[196:197], v[204:205]
	v_pk_mul_f32 v[206:207], v[198:199], v[206:207]
	v_pk_mul_f32 v[208:209], v[200:201], v[208:209]
	v_pk_mul_f32 v[202:203], v[202:203], v[238:239] op_sel_hi:[1,0]
	v_pk_mul_f32 v[204:205], v[204:205], v[238:239] op_sel_hi:[1,0]
	v_pk_mul_f32 v[206:207], v[206:207], v[238:239] op_sel_hi:[1,0]
	v_pk_mul_f32 v[208:209], v[208:209], v[238:239] op_sel_hi:[1,0]
	v_exp_f32_e32 v202, v202
	v_exp_f32_e32 v203, v203
	v_exp_f32_e32 v204, v204
	v_exp_f32_e32 v205, v205
	v_exp_f32_e32 v206, v206
	v_exp_f32_e32 v207, v207
	v_exp_f32_e32 v208, v208
	v_exp_f32_e32 v209, v209
	v_pk_add_f32 v[202:203], v[202:203], v[238:239] op_sel:[0,1] op_sel_hi:[1,1]
	v_pk_add_f32 v[204:205], v[204:205], v[238:239] op_sel:[0,1] op_sel_hi:[1,1]
	v_pk_add_f32 v[206:207], v[206:207], v[238:239] op_sel:[0,1] op_sel_hi:[1,1]
	v_pk_add_f32 v[208:209], v[208:209], v[238:239] op_sel:[0,1] op_sel_hi:[1,1]
	v_rcp_f32_e32 v202, v202
	v_rcp_f32_e32 v203, v203
	v_rcp_f32_e32 v204, v204
	v_rcp_f32_e32 v205, v205
	v_rcp_f32_e32 v206, v206
	v_rcp_f32_e32 v207, v207
	v_rcp_f32_e32 v208, v208
	v_rcp_f32_e32 v209, v209
	v_pk_mul_f32 v[194:195], v[194:195], v[202:203]
	v_pk_mul_f32 v[196:197], v[196:197], v[204:205]
	v_pk_mul_f32 v[198:199], v[198:199], v[206:207]
	v_pk_mul_f32 v[200:201], v[200:201], v[208:209]
	v_pk_mul_f32 v[106:107], v[106:107], v[194:195]
	v_pk_mul_f32 v[108:109], v[108:109], v[196:197]
	v_pk_mul_f32 v[98:99], v[98:99], v[198:199]
	v_pk_mul_f32 v[100:101], v[100:101], v[200:201]
	v_cvt_pk_bf16_f32 v106, v106, v107
	v_cvt_pk_bf16_f32 v107, v108, v109
	v_cvt_pk_bf16_f32 v108, v98, v99
	v_cvt_pk_bf16_f32 v109, v100, v101
	global_store_dwordx4 v[234:235], v[106:109], off
	v_pk_mul_f32 v[202:203], v[134:135], v[94:95]
	v_pk_mul_f32 v[204:205], v[136:137], v[96:97]
	v_pk_mul_f32 v[206:207], v[122:123], v[86:87]
	v_pk_mul_f32 v[208:209], v[124:125], v[88:89]
	s_mov_b64 s[6:7], 0x6000
	v_lshl_add_u64 v[232:233], v[192:193], 0, s[6:7]
	v_pk_fma_f32 v[202:203], v[78:79], v[70:71], v[202:203]
	v_pk_fma_f32 v[204:205], v[80:81], v[72:73], v[204:205]
	v_pk_fma_f32 v[206:207], v[62:63], v[54:55], v[206:207]
	v_pk_fma_f32 v[208:209], v[64:65], v[56:57], v[208:209]
	v_pk_fma_f32 v[194:195], v[82:83], v[46:47], v[202:203]
	v_pk_fma_f32 v[196:197], v[84:85], v[48:49], v[204:205]
	v_pk_fma_f32 v[198:199], v[66:67], v[38:39], v[206:207]
	v_pk_fma_f32 v[200:201], v[68:69], v[40:41], v[208:209]
	v_pk_mul_f32 v[202:203], v[194:195], v[236:237] op_sel_hi:[1,0]
	v_pk_mul_f32 v[204:205], v[196:197], v[236:237] op_sel_hi:[1,0]
	v_pk_mul_f32 v[206:207], v[198:199], v[236:237] op_sel_hi:[1,0]
	v_pk_mul_f32 v[208:209], v[200:201], v[236:237] op_sel_hi:[1,0]
	v_pk_fma_f32 v[202:203], v[194:195], v[202:203], v[236:237] op_sel:[0,0,1] op_sel_hi:[1,1,1]
	v_pk_fma_f32 v[204:205], v[196:197], v[204:205], v[236:237] op_sel:[0,0,1] op_sel_hi:[1,1,1]
	v_pk_fma_f32 v[206:207], v[198:199], v[206:207], v[236:237] op_sel:[0,0,1] op_sel_hi:[1,1,1]
	v_pk_fma_f32 v[208:209], v[200:201], v[208:209], v[236:237] op_sel:[0,0,1] op_sel_hi:[1,1,1]
	v_pk_mul_f32 v[202:203], v[194:195], v[202:203]
	v_pk_mul_f32 v[204:205], v[196:197], v[204:205]
	v_pk_mul_f32 v[206:207], v[198:199], v[206:207]
	v_pk_mul_f32 v[208:209], v[200:201], v[208:209]
	v_pk_mul_f32 v[202:203], v[202:203], v[238:239] op_sel_hi:[1,0]
	v_pk_mul_f32 v[204:205], v[204:205], v[238:239] op_sel_hi:[1,0]
	v_pk_mul_f32 v[206:207], v[206:207], v[238:239] op_sel_hi:[1,0]
	v_pk_mul_f32 v[208:209], v[208:209], v[238:239] op_sel_hi:[1,0]
	v_exp_f32_e32 v202, v202
	v_exp_f32_e32 v203, v203
	v_exp_f32_e32 v204, v204
	v_exp_f32_e32 v205, v205
	v_exp_f32_e32 v206, v206
	v_exp_f32_e32 v207, v207
	v_exp_f32_e32 v208, v208
	v_exp_f32_e32 v209, v209
	v_pk_add_f32 v[202:203], v[202:203], v[238:239] op_sel:[0,1] op_sel_hi:[1,1]
	v_pk_add_f32 v[204:205], v[204:205], v[238:239] op_sel:[0,1] op_sel_hi:[1,1]
	v_pk_add_f32 v[206:207], v[206:207], v[238:239] op_sel:[0,1] op_sel_hi:[1,1]
	v_pk_add_f32 v[208:209], v[208:209], v[238:239] op_sel:[0,1] op_sel_hi:[1,1]
	v_rcp_f32_e32 v202, v202
	v_rcp_f32_e32 v203, v203
	v_rcp_f32_e32 v204, v204
	v_rcp_f32_e32 v205, v205
	v_rcp_f32_e32 v206, v206
	v_rcp_f32_e32 v207, v207
	v_rcp_f32_e32 v208, v208
	v_rcp_f32_e32 v209, v209
	v_pk_mul_f32 v[194:195], v[194:195], v[202:203]
	v_pk_mul_f32 v[196:197], v[196:197], v[204:205]
	v_pk_mul_f32 v[198:199], v[198:199], v[206:207]
	v_pk_mul_f32 v[200:201], v[200:201], v[208:209]
	v_pk_mul_f32 v[90:91], v[90:91], v[194:195]
	v_pk_mul_f32 v[92:93], v[92:93], v[196:197]
	v_pk_mul_f32 v[74:75], v[74:75], v[198:199]
	v_pk_mul_f32 v[76:77], v[76:77], v[200:201]
	v_cvt_pk_bf16_f32 v90, v90, v91
	v_cvt_pk_bf16_f32 v91, v92, v93
	v_cvt_pk_bf16_f32 v92, v74, v75
	v_cvt_pk_bf16_f32 v93, v76, v77
	global_store_dwordx4 v[232:233], v[90:93], off
	v_pk_mul_f32 v[202:203], v[134:135], v[70:71]
	v_pk_mul_f32 v[204:205], v[136:137], v[72:73]
	v_pk_mul_f32 v[206:207], v[122:123], v[54:55]
	v_pk_mul_f32 v[208:209], v[124:125], v[56:57]
	s_mov_b64 s[6:7], 0x7800
	v_lshl_add_u64 v[234:235], v[192:193], 0, s[6:7]
	v_pk_fma_f32 v[202:203], v[78:79], v[46:47], v[202:203]
	v_pk_fma_f32 v[204:205], v[80:81], v[48:49], v[204:205]
	v_pk_fma_f32 v[206:207], v[62:63], v[38:39], v[206:207]
	v_pk_fma_f32 v[208:209], v[64:65], v[40:41], v[208:209]
	v_pk_fma_f32 v[194:195], v[82:83], v[30:31], v[202:203]
	v_pk_fma_f32 v[196:197], v[84:85], v[32:33], v[204:205]
	v_pk_fma_f32 v[198:199], v[66:67], v[14:15], v[206:207]
	v_pk_fma_f32 v[200:201], v[68:69], v[16:17], v[208:209]
	v_pk_mul_f32 v[202:203], v[194:195], v[236:237] op_sel_hi:[1,0]
	v_pk_mul_f32 v[204:205], v[196:197], v[236:237] op_sel_hi:[1,0]
; DEV u32x4 pack8(const float (&f)[8]) { u32x4 w; w.x = cvt_pk_bf16(f[0], f[1]); w.y = cvt_pk_bf16(f[2], f[3]); w.z = cvt_pk_bf16(f[4], f[5]); w.w = cvt_pk_bf16(f[6], f[7]); return w; }
; DEV float gelu_t(float x) { const float u = x * (0.7978845608f + 0.0356774081f * x * x); return x * __builtin_amdgcn_rcpf(1.f + __builtin_amdgcn_exp2f(-2.885390082f * u)); }
;     DEV bool operator()(f32x4 (&acc)[2][2][4][2], const Unit& u, int wr, int wc, int fr, int fq) const {
;     ...
;         for (int i = 0; i < 8; ++i) { float y[8];
; #pragma unroll
;             for (int c = 0; c < 8; ++c) {
;                 const float g0 = acc[i >> 2][0][i & 3][c >> 2][c & 3];
;                 const float gm1 = i >= 1 ? acc[(i - 1 < 0 ? 0 : i - 1) >> 2][0][(i - 1 < 0 ? 0 : i - 1) & 3][c >> 2][c & 3] : p7[c];
;                 const float gm2 = i >= 2 ? acc[(i - 2 < 0 ? 0 : i - 2) >> 2][0][(i - 2 < 0 ? 0 : i - 2) & 3][c >> 2][c & 3] : (i == 0 ? p6[c] : p7[c]);
;                 y[c] = gelu_t(w[0][c] * gm2 + w[1][c] * gm1 + w[2][c] * g0) * acc[i >> 2][1][i & 3][c >> 2][c & 3]; }
;             if (!(halo && i < 2)) *(u32x4*)(outp + (size_t)i * DFF) = pack8(y); }
	v_pk_mul_f32 v[206:207], v[198:199], v[236:237] op_sel_hi:[1,0]
	v_pk_mul_f32 v[208:209], v[200:201], v[236:237] op_sel_hi:[1,0]
	v_pk_fma_f32 v[202:203], v[194:195], v[202:203], v[236:237] op_sel:[0,0,1] op_sel_hi:[1,1,1]
	v_pk_fma_f32 v[204:205], v[196:197], v[204:205], v[236:237] op_sel:[0,0,1] op_sel_hi:[1,1,1]
	v_pk_fma_f32 v[206:207], v[198:199], v[206:207], v[236:237] op_sel:[0,0,1] op_sel_hi:[1,1,1]
	v_pk_fma_f32 v[208:209], v[200:201], v[208:209], v[236:237] op_sel:[0,0,1] op_sel_hi:[1,1,1]
	v_pk_mul_f32 v[202:203], v[194:195], v[202:203]
	v_pk_mul_f32 v[204:205], v[196:197], v[204:205]
	v_pk_mul_f32 v[206:207], v[198:199], v[206:207]
	v_pk_mul_f32 v[208:209], v[200:201], v[208:209]
	v_pk_mul_f32 v[202:203], v[202:203], v[238:239] op_sel_hi:[1,0]
	v_pk_mul_f32 v[204:205], v[204:205], v[238:239] op_sel_hi:[1,0]
	v_pk_mul_f32 v[206:207], v[206:207], v[238:239] op_sel_hi:[1,0]
	v_pk_mul_f32 v[208:209], v[208:209], v[238:239] op_sel_hi:[1,0]
	v_exp_f32_e32 v202, v202
	v_exp_f32_e32 v203, v203
	v_exp_f32_e32 v204, v204
	v_exp_f32_e32 v205, v205
	v_exp_f32_e32 v206, v206
	v_exp_f32_e32 v207, v207
	v_exp_f32_e32 v208, v208
	v_exp_f32_e32 v209, v209
	v_pk_add_f32 v[202:203], v[202:203], v[238:239] op_sel:[0,1] op_sel_hi:[1,1]
	v_pk_add_f32 v[204:205], v[204:205], v[238:239] op_sel:[0,1] op_sel_hi:[1,1]
	v_pk_add_f32 v[206:207], v[206:207], v[238:239] op_sel:[0,1] op_sel_hi:[1,1]
	v_pk_add_f32 v[208:209], v[208:209], v[238:239] op_sel:[0,1] op_sel_hi:[1,1]
	v_rcp_f32_e32 v202, v202
	v_rcp_f32_e32 v203, v203
	v_rcp_f32_e32 v204, v204
	v_rcp_f32_e32 v205, v205
	v_rcp_f32_e32 v206, v206
	v_rcp_f32_e32 v207, v207
	v_rcp_f32_e32 v208, v208
	v_rcp_f32_e32 v209, v209
	v_pk_mul_f32 v[194:195], v[194:195], v[202:203]
	v_pk_mul_f32 v[196:197], v[196:197], v[204:205]
	v_pk_mul_f32 v[198:199], v[198:199], v[206:207]
	v_pk_mul_f32 v[200:201], v[200:201], v[208:209]
	v_pk_mul_f32 v[58:59], v[58:59], v[194:195]
	v_pk_mul_f32 v[60:61], v[60:61], v[196:197]
	v_pk_mul_f32 v[50:51], v[50:51], v[198:199]
	v_pk_mul_f32 v[52:53], v[52:53], v[200:201]
	v_cvt_pk_bf16_f32 v58, v58, v59
	v_cvt_pk_bf16_f32 v59, v60, v61
	v_cvt_pk_bf16_f32 v60, v50, v51
	v_cvt_pk_bf16_f32 v61, v52, v53
	global_store_dwordx4 v[234:235], v[58:61], off
	v_pk_mul_f32 v[202:203], v[134:135], v[46:47]
	v_pk_mul_f32 v[204:205], v[136:137], v[48:49]
	v_pk_mul_f32 v[206:207], v[122:123], v[38:39]
	v_pk_mul_f32 v[208:209], v[124:125], v[40:41]
	s_mov_b64 s[6:7], 0x9000
	v_lshl_add_u64 v[232:233], v[192:193], 0, s[6:7]
	v_pk_fma_f32 v[202:203], v[78:79], v[30:31], v[202:203]
	v_pk_fma_f32 v[204:205], v[80:81], v[32:33], v[204:205]
	v_pk_fma_f32 v[206:207], v[62:63], v[14:15], v[206:207]
	v_pk_fma_f32 v[208:209], v[64:65], v[16:17], v[208:209]
	v_pk_fma_f32 v[194:195], v[82:83], v[26:27], v[202:203]
	v_pk_fma_f32 v[196:197], v[84:85], v[28:29], v[204:205]
	v_pk_fma_f32 v[198:199], v[66:67], v[10:11], v[206:207]
	v_pk_fma_f32 v[200:201], v[68:69], v[12:13], v[208:209]
	v_pk_mul_f32 v[202:203], v[194:195], v[236:237] op_sel_hi:[1,0]
	v_pk_mul_f32 v[204:205], v[196:197], v[236:237] op_sel_hi:[1,0]
	v_pk_mul_f32 v[206:207], v[198:199], v[236:237] op_sel_hi:[1,0]
	v_pk_mul_f32 v[208:209], v[200:201], v[236:237] op_sel_hi:[1,0]
	v_pk_fma_f32 v[202:203], v[194:195], v[202:203], v[236:237] op_sel:[0,0,1] op_sel_hi:[1,1,1]
	v_pk_fma_f32 v[204:205], v[196:197], v[204:205], v[236:237] op_sel:[0,0,1] op_sel_hi:[1,1,1]
	v_pk_fma_f32 v[206:207], v[198:199], v[206:207], v[236:237] op_sel:[0,0,1] op_sel_hi:[1,1,1]
	v_pk_fma_f32 v[208:209], v[200:201], v[208:209], v[236:237] op_sel:[0,0,1] op_sel_hi:[1,1,1]
	v_pk_mul_f32 v[202:203], v[194:195], v[202:203]
	v_pk_mul_f32 v[204:205], v[196:197], v[204:205]
	v_pk_mul_f32 v[206:207], v[198:199], v[206:207]
	v_pk_mul_f32 v[208:209], v[200:201], v[208:209]
	v_pk_mul_f32 v[202:203], v[202:203], v[238:239] op_sel_hi:[1,0]
	v_pk_mul_f32 v[204:205], v[204:205], v[238:239] op_sel_hi:[1,0]
	v_pk_mul_f32 v[206:207], v[206:207], v[238:239] op_sel_hi:[1,0]
	v_pk_mul_f32 v[208:209], v[208:209], v[238:239] op_sel_hi:[1,0]
	v_exp_f32_e32 v202, v202
	v_exp_f32_e32 v203, v203
	v_exp_f32_e32 v204, v204
	v_exp_f32_e32 v205, v205
	v_exp_f32_e32 v206, v206
	v_exp_f32_e32 v207, v207
	v_exp_f32_e32 v208, v208
	v_exp_f32_e32 v209, v209
	v_pk_add_f32 v[202:203], v[202:203], v[238:239] op_sel:[0,1] op_sel_hi:[1,1]
; DEV float gelu_t(float x) { const float u = x * (0.7978845608f + 0.0356774081f * x * x); return x * __builtin_amdgcn_rcpf(1.f + __builtin_amdgcn_exp2f(-2.885390082f * u)); }
; DEV u32x4 pack8(const float (&f)[8]) { u32x4 w; w.x = cvt_pk_bf16(f[0], f[1]); w.y = cvt_pk_bf16(f[2], f[3]); w.z = cvt_pk_bf16(f[4], f[5]); w.w = cvt_pk_bf16(f[6], f[7]); return w; }
; #define PG8_BAR __builtin_amdgcn_s_barrier()
;     DEV bool operator()(f32x4 (&acc)[2][2][4][2], const Unit& u, int wr, int wc, int fr, int fq) const {
;     ...
;         for (int i = 0; i < 8; ++i) { float y[8];
; #pragma unroll
;             for (int c = 0; c < 8; ++c) {
;                 const float g0 = acc[i >> 2][0][i & 3][c >> 2][c & 3];
;                 const float gm1 = i >= 1 ? acc[(i - 1 < 0 ? 0 : i - 1) >> 2][0][(i - 1 < 0 ? 0 : i - 1) & 3][c >> 2][c & 3] : p7[c];
;                 const float gm2 = i >= 2 ? acc[(i - 2 < 0 ? 0 : i - 2) >> 2][0][(i - 2 < 0 ? 0 : i - 2) & 3][c >> 2][c & 3] : (i == 0 ? p6[c] : p7[c]);
;                 y[c] = gelu_t(w[0][c] * gm2 + w[1][c] * gm1 + w[2][c] * g0) * acc[i >> 2][1][i & 3][c >> 2][c & 3]; }
;             if (!(halo && i < 2)) *(u32x4*)(outp + (size_t)i * DFF) = pack8(y); }
; template <bool ALIGN_EPI, class Epi, class Sched>
; DEV void gemm_phase(LAS unsigned char* lds, const Gemm g, const Sched& S, const Epi& E) {
;     ...
;         if (!has_next) break;
;         if (rst) {
; #pragma unroll
;         for (int a = 0; a < 2; ++a)
; #pragma unroll
;             for (int b = 0; b < 2; ++b)
; #pragma unroll
;                 for (int m = 0; m < 4; ++m)
; #pragma unroll
;                     for (int n = 0; n < 2; ++n) acc[a][b][m][n] = (f32x4){0.f, 0.f, 0.f, 0.f}; }
;         cur = nxt; cA = nA; cB = nB; ++ui;
;         if (ALIGN_EPI) { if (wr == 1) PG8_BAR; }
	v_pk_add_f32 v[204:205], v[204:205], v[238:239] op_sel:[0,1] op_sel_hi:[1,1]
	v_pk_add_f32 v[206:207], v[206:207], v[238:239] op_sel:[0,1] op_sel_hi:[1,1]
	v_pk_add_f32 v[208:209], v[208:209], v[238:239] op_sel:[0,1] op_sel_hi:[1,1]
	v_rcp_f32_e32 v202, v202
	v_rcp_f32_e32 v203, v203
	v_rcp_f32_e32 v204, v204
	v_rcp_f32_e32 v205, v205
	v_rcp_f32_e32 v206, v206
	v_rcp_f32_e32 v207, v207
	v_rcp_f32_e32 v208, v208
	v_rcp_f32_e32 v209, v209
	v_pk_mul_f32 v[194:195], v[194:195], v[202:203]
	v_pk_mul_f32 v[196:197], v[196:197], v[204:205]
	v_pk_mul_f32 v[198:199], v[198:199], v[206:207]
	v_pk_mul_f32 v[200:201], v[200:201], v[208:209]
	v_pk_mul_f32 v[42:43], v[42:43], v[194:195]
	v_pk_mul_f32 v[44:45], v[44:45], v[196:197]
	v_pk_mul_f32 v[34:35], v[34:35], v[198:199]
	v_pk_mul_f32 v[36:37], v[36:37], v[200:201]
	v_cvt_pk_bf16_f32 v42, v42, v43
	v_cvt_pk_bf16_f32 v43, v44, v45
	v_cvt_pk_bf16_f32 v44, v34, v35
	v_cvt_pk_bf16_f32 v45, v36, v37
	global_store_dwordx4 v[232:233], v[42:45], off
	v_pk_mul_f32 v[202:203], v[134:135], v[30:31]
	v_pk_mul_f32 v[204:205], v[136:137], v[32:33]
	v_pk_mul_f32 v[206:207], v[122:123], v[14:15]
	v_pk_mul_f32 v[208:209], v[124:125], v[16:17]
	s_mov_b64 s[6:7], 0xa800
	v_lshl_add_u64 v[234:235], v[192:193], 0, s[6:7]
	v_pk_fma_f32 v[202:203], v[78:79], v[26:27], v[202:203]
	v_pk_fma_f32 v[204:205], v[80:81], v[28:29], v[204:205]
	v_pk_fma_f32 v[206:207], v[62:63], v[10:11], v[206:207]
	v_pk_fma_f32 v[208:209], v[64:65], v[12:13], v[208:209]
	v_pk_fma_f32 v[194:195], v[82:83], v[22:23], v[202:203]
	v_pk_fma_f32 v[196:197], v[84:85], v[24:25], v[204:205]
	v_pk_fma_f32 v[198:199], v[66:67], v[6:7], v[206:207]
	v_pk_fma_f32 v[200:201], v[68:69], v[8:9], v[208:209]
	v_pk_mul_f32 v[202:203], v[194:195], v[236:237] op_sel_hi:[1,0]
	v_pk_mul_f32 v[204:205], v[196:197], v[236:237] op_sel_hi:[1,0]
	v_pk_mul_f32 v[206:207], v[198:199], v[236:237] op_sel_hi:[1,0]
	v_pk_mul_f32 v[208:209], v[200:201], v[236:237] op_sel_hi:[1,0]
	v_pk_fma_f32 v[202:203], v[194:195], v[202:203], v[236:237] op_sel:[0,0,1] op_sel_hi:[1,1,1]
	v_pk_fma_f32 v[204:205], v[196:197], v[204:205], v[236:237] op_sel:[0,0,1] op_sel_hi:[1,1,1]
	v_pk_fma_f32 v[206:207], v[198:199], v[206:207], v[236:237] op_sel:[0,0,1] op_sel_hi:[1,1,1]
	v_pk_fma_f32 v[208:209], v[200:201], v[208:209], v[236:237] op_sel:[0,0,1] op_sel_hi:[1,1,1]
	v_pk_mul_f32 v[202:203], v[194:195], v[202:203]
	v_pk_mul_f32 v[204:205], v[196:197], v[204:205]
	v_pk_mul_f32 v[206:207], v[198:199], v[206:207]
	v_pk_mul_f32 v[208:209], v[200:201], v[208:209]
	v_pk_mul_f32 v[202:203], v[202:203], v[238:239] op_sel_hi:[1,0]
	v_pk_mul_f32 v[204:205], v[204:205], v[238:239] op_sel_hi:[1,0]
	v_pk_mul_f32 v[206:207], v[206:207], v[238:239] op_sel_hi:[1,0]
	v_pk_mul_f32 v[208:209], v[208:209], v[238:239] op_sel_hi:[1,0]
	v_exp_f32_e32 v202, v202
	v_exp_f32_e32 v203, v203
	v_exp_f32_e32 v204, v204
	v_exp_f32_e32 v205, v205
	v_exp_f32_e32 v206, v206
	v_exp_f32_e32 v207, v207
	v_exp_f32_e32 v208, v208
	v_exp_f32_e32 v209, v209
	v_pk_add_f32 v[202:203], v[202:203], v[238:239] op_sel:[0,1] op_sel_hi:[1,1]
	v_pk_add_f32 v[204:205], v[204:205], v[238:239] op_sel:[0,1] op_sel_hi:[1,1]
	v_pk_add_f32 v[206:207], v[206:207], v[238:239] op_sel:[0,1] op_sel_hi:[1,1]
	v_pk_add_f32 v[208:209], v[208:209], v[238:239] op_sel:[0,1] op_sel_hi:[1,1]
	v_rcp_f32_e32 v202, v202
	v_rcp_f32_e32 v203, v203
	v_rcp_f32_e32 v204, v204
	v_rcp_f32_e32 v205, v205
	v_rcp_f32_e32 v206, v206
	v_rcp_f32_e32 v207, v207
	v_rcp_f32_e32 v208, v208
	v_rcp_f32_e32 v209, v209
	v_pk_mul_f32 v[194:195], v[194:195], v[202:203]
	v_pk_mul_f32 v[196:197], v[196:197], v[204:205]
	v_pk_mul_f32 v[198:199], v[198:199], v[206:207]
	v_pk_mul_f32 v[200:201], v[200:201], v[208:209]
	v_pk_mul_f32 v[18:19], v[18:19], v[194:195]
	v_pk_mul_f32 v[20:21], v[20:21], v[196:197]
	v_pk_mul_f32 v[2:3], v[2:3], v[198:199]
	v_pk_mul_f32 v[4:5], v[4:5], v[200:201]
	v_cvt_pk_bf16_f32 v18, v18, v19
	v_cvt_pk_bf16_f32 v19, v20, v21
	v_cvt_pk_bf16_f32 v20, v2, v3
	v_cvt_pk_bf16_f32 v21, v4, v5
	global_store_dwordx4 v[234:235], v[18:21], off
	s_mov_b64 s[4:5], -1
	s_andn2_b64 vcc, exec, s[44:45]
	s_cbranch_vccnz .LBB0_24
	v_readlane_b32 s4, v255, 4
	v_readlane_b32 s5, v255, 5
	s_andn2_b64 vcc, exec, s[4:5]
	s_cbranch_vccnz .LBB0_23
	s_barrier
	s_branch .LBB0_23
